# prep_gla V-transpose moved onto waves idle during prep_ssd B/C body (x4 row loads + v_perm in-lane transpose); compiled all-wave version's loads/stores removed
# baseline (speedup 1.0000x reference)
; __device__ __forceinline__ unsigned pk2(float lo, float hi) { const f32v2_t v = {lo, hi}; const bf16v2_t b = __builtin_convertvector(v, bf16v2_t); return __builtin_bit_cast(unsigned, b); }
; __device__ __forceinline__ float siluf_(float x) { return x * __builtin_amdgcn_rcpf(1.0f + __expf(-x)); }
; __device__ void prep_ssd(const Ctx& c, int ck, int blk) {
;     ...
;         for (int l0 = 0; l0 < 64; l0 += 8) {
;             float xv[8];
; #pragma unroll
;             for (int j = 0; j < 8; ++j) { const int l = l0 + j;
;                 const float xc = raw[l];
;                 const float y = w0 * xm3 + w1 * xm2 + w2 * xm1 + w3 * xc + bb; xm3 = xm2; xm2 = xm1; xm1 = xc;
;                 const float x = siluf_(y); xv[j] = x;
;                 rowdst[(size_t)(t0 + l) * 256 + cc] = f2bf(x); }
;             if (!isC) { u32x4 a; a.x = pk2(xv[0], xv[1]); a.y = pk2(xv[2], xv[3]); a.z = pk2(xv[4], xv[5]); a.w = pk2(xv[6], xv[7]);
;                 *(u32x4*)(sBT + ((size_t)(ck * 2 + g) * 128 + n) * 64 + l0) = a; }
;         }
.LBB0_657:
	s_or_b64 exec, exec, s[0:1]
	v_pk_mul_f32 v[22:23], v[2:3], v[28:29]
	v_lshlrev_b32_e32 v26, 16, v39
	v_lshlrev_b32_e32 v27, 16, v40
	v_pk_fma_f32 v[22:23], v[0:1], v[24:25], v[22:23]
	v_pk_mov_b32 v[24:25], v[14:15], v[26:27] op_sel:[1,0]
	v_pk_fma_f32 v[22:23], v[4:5], v[14:15], v[22:23]
	v_lshlrev_b32_e32 v29, 16, v34
	v_pk_fma_f32 v[22:23], v[6:7], v[24:25], v[22:23]
	v_lshlrev_b32_e32 v33, 16, v35
	v_pk_add_f32 v[22:23], v[8:9], v[22:23]
	v_pk_mul_f32 v[24:25], v[2:3], v[24:25]
	v_mul_f32_e32 v21, 0xbfb8aa3b, v22
	v_exp_f32_e32 v21, v21
	v_mul_f32_e32 v28, 0xbfb8aa3b, v23
	v_exp_f32_e32 v28, v28
	v_lshlrev_b32_e32 v30, 16, v37
	v_add_f32_e32 v21, 1.0, v21
	v_rcp_f32_e32 v34, v21
	v_add_f32_e32 v21, 1.0, v28
	v_rcp_f32_e32 v35, v21
	v_lshlrev_b32_e32 v31, 16, v38
	v_pk_fma_f32 v[14:15], v[0:1], v[14:15], v[24:25]
	v_pk_mov_b32 v[24:25], v[26:27], v[30:31] op_sel:[1,0]
	v_pk_fma_f32 v[14:15], v[4:5], v[26:27], v[14:15]
	s_lshl_b64 s[0:1], s[14:15], 9
	v_pk_fma_f32 v[14:15], v[6:7], v[24:25], v[14:15]
	v_pk_mul_f32 v[22:23], v[22:23], v[34:35]
	v_pk_add_f32 v[14:15], v[8:9], v[14:15]
	v_lshl_add_u64 v[38:39], v[10:11], 0, s[0:1]
	v_cvt_pk_bf16_f32 v21, v22, s0
	v_mul_f32_e32 v34, 0xbfb8aa3b, v14
	global_store_short v[38:39], v21, off
	v_exp_f32_e32 v38, v34
	v_mul_f32_e32 v34, 0xbfb8aa3b, v15
	v_exp_f32_e32 v39, v34
	v_pk_mul_f32 v[24:25], v[2:3], v[24:25]
	v_add_f32_e32 v38, 1.0, v38
	v_rcp_f32_e32 v38, v38
	v_add_f32_e32 v39, 1.0, v39
	v_rcp_f32_e32 v39, v39
	v_lshlrev_b32_e32 v32, 16, v36
	v_pk_fma_f32 v[24:25], v[0:1], v[26:27], v[24:25]
	v_mov_b32_e32 v36, v31
	v_mov_b32_e32 v37, v32
	v_pk_fma_f32 v[24:25], v[4:5], v[30:31], v[24:25]
	v_pk_mov_b32 v[26:27], v[30:31], v[32:33] op_sel:[1,0]
	v_cvt_pk_bf16_f32 v21, v23, s0
	s_lshl_b64 s[0:1], s[84:85], 9
	v_pk_fma_f32 v[24:25], v[6:7], v[26:27], v[24:25]
	v_pk_mul_f32 v[2:3], v[2:3], v[36:37]
	v_lshl_add_u64 v[34:35], v[10:11], 0, s[0:1]
	s_lshl_b64 s[0:1], s[40:41], 9
	v_pk_mul_f32 v[14:15], v[14:15], v[38:39]
	v_pk_add_f32 v[24:25], v[8:9], v[24:25]
	v_pk_fma_f32 v[0:1], v[0:1], v[30:31], v[2:3]
	v_mov_b32_e32 v28, v33
	global_store_short v[34:35], v21, off
	v_lshl_add_u64 v[34:35], v[10:11], 0, s[0:1]
	v_cvt_pk_bf16_f32 v21, v14, s0
	v_mul_f32_e32 v26, 0xbfb8aa3b, v24
	v_pk_fma_f32 v[0:1], v[4:5], v[32:33], v[0:1]
	global_store_short v[34:35], v21, off
	v_exp_f32_e32 v34, v26
	v_mul_f32_e32 v26, 0xbfb8aa3b, v25
	v_pk_fma_f32 v[0:1], v[6:7], v[28:29], v[0:1]
	v_exp_f32_e32 v35, v26
	v_pk_add_f32 v[0:1], v[8:9], v[0:1]
	v_add_f32_e32 v34, 1.0, v34
	v_mul_f32_e32 v2, 0xbfb8aa3b, v0
	v_exp_f32_e32 v4, v2
	v_mul_f32_e32 v2, 0xbfb8aa3b, v1
	v_exp_f32_e32 v5, v2
	v_add_f32_e32 v35, 1.0, v35
	v_rcp_f32_e32 v34, v34
	v_rcp_f32_e32 v35, v35
	v_add_f32_e32 v4, 1.0, v4
	v_add_f32_e32 v5, 1.0, v5
	v_cvt_pk_bf16_f32 v21, v15, s0
	s_lshl_b64 s[0:1], s[10:11], 9
	v_rcp_f32_e32 v4, v4
	v_rcp_f32_e32 v5, v5
	v_lshl_add_u64 v[26:27], v[10:11], 0, s[0:1]
	s_lshl_b64 s[0:1], s[12:13], 9
	v_pk_mul_f32 v[24:25], v[24:25], v[34:35]
	global_store_short v[26:27], v21, off
	v_lshl_add_u64 v[26:27], v[10:11], 0, s[0:1]
	v_cvt_pk_bf16_f32 v21, v24, s0
	global_store_short v[26:27], v21, off
	v_cvt_pk_bf16_f32 v21, v25, s0
	s_lshl_b64 s[0:1], s[74:75], 9
	v_lshl_add_u64 v[2:3], v[10:11], 0, s[0:1]
	s_lshl_b64 s[0:1], s[68:69], 9
	v_pk_mul_f32 v[0:1], v[0:1], v[4:5]
	global_store_short v[2:3], v21, off
	v_lshl_add_u64 v[2:3], v[10:11], 0, s[0:1]
	v_cvt_pk_bf16_f32 v4, v0, s0
	global_store_short v[2:3], v4, off
	v_cvt_pk_bf16_f32 v4, v1, s0
	s_lshl_b64 s[0:1], s[66:67], 9
	v_lshl_add_u64 v[2:3], v[10:11], 0, s[0:1]
	global_store_short v[2:3], v4, off
	s_and_saveexec_b64 s[0:1], vcc
	s_cbranch_execz .LBB0_659
	v_cvt_pk_bf16_f32 v2, v22, v23
	v_cvt_pk_bf16_f32 v3, v14, v15
	v_cvt_pk_bf16_f32 v4, v24, v25
	v_cvt_pk_bf16_f32 v5, v0, v1
	global_store_dwordx4 v[12:13], v[2:5], off offset:112
.LBB0_659:
	s_or_b64 exec, exec, s[0:1]
	s_branch .LBB0_660
; #define PIN16(a, o) asm volatile("" : "+v"(a[(o)+0]), "+v"(a[(o)+1]), "+v"(a[(o)+2]), "+v"(a[(o)+3]), "+v"(a[(o)+4]), "+v"(a[(o)+5]), "+v"(a[(o)+6]), "+v"(a[(o)+7]), \
;     "+v"(a[(o)+8]), "+v"(a[(o)+9]), "+v"(a[(o)+10]), "+v"(a[(o)+11]), "+v"(a[(o)+12]), "+v"(a[(o)+13]), "+v"(a[(o)+14]), "+v"(a[(o)+15]))
;     template <class Tp> __device__ __forceinline__ Tp* W(size_t off) const { return (Tp*)(ws + off); }
; __device__ void prep_gla(const Ctx& c, int ck, int blk) {
;     ...
;         const int ch = (blk - 1) * 512 + tid, h = ch >> 8, v = ch & 255;
;         bf16_t* gVT = c.W<bf16_t>(WS_GVT);
;         unsigned e[64];
; #pragma unroll
;         for (int l = 0; l < 64; ++l) e[l] = proj[(size_t)(t0 + l) * NP + C_GV + ch];
;         PIN16(e, 0); PIN16(e, 16); PIN16(e, 32); PIN16(e, 48);
; #pragma unroll
;         for (int l0 = 0; l0 < 64; l0 += 8) {
;             u32x4 a; a.x = e[l0] | (e[l0 + 1] << 16); a.y = e[l0 + 2] | (e[l0 + 3] << 16); a.z = e[l0 + 4] | (e[l0 + 5] << 16); a.w = e[l0 + 6] | (e[l0 + 7] << 16);
;             *(u32x4*)(gVT + ((size_t)(ck * 4 + h) * 256 + v) * 64 + l0) = a;
;         }
.Lglb_entry:
	s_mov_b64 exec, -1
	v_readlane_b32 s2, v249, 32
	v_readlane_b32 s3, v249, 33
	v_readlane_b32 s20, v249, 38
	v_readlane_b32 s21, v249, 37
	v_lshrrev_b32_e32 v2, 6, v144
	s_nop 1
	s_load_dwordx2 s[0:1], s[2:3], 0xe8
	v_readfirstlane_b32 s24, v2
	s_lshl_b32 s25, s21, 9
	s_nop 0
	s_sub_u32 s24, s24, 4
	v_lshl_add_u32 v2, v237, 3, s25
	v_lshlrev_b32_e32 v0, 1, v2
	v_add_u32_e32 v0, 0x3c40, v0
	s_lshl_b32 s26, s20, 10
	v_add_u32_e32 v1, s26, v2
	v_lshlrev_b32_e32 v1, 7, v1
	s_lshl_b32 s27, s24, 5
	v_add_u32_e32 v1, s27, v1
	v_add_u32_e32 v1, 0x31d81000, v1
	s_lshl_b32 s26, s20, 6
	s_lshl_b32 s27, s24, 4
	s_add_u32 s26, s26, s27
	s_mul_i32 s26, s26, 0x7e00
	s_waitcnt lgkmcnt(0)
	s_add_u32 s30, s0, s26
	s_addc_u32 s31, s1, 0
	s_add_u32 s30, s30, 0x9c00000
	s_addc_u32 s31, s31, 0
	global_load_dwordx4 v[24:27], v0, s[30:31]
	s_add_u32 s30, s30, 0x7e00
	s_addc_u32 s31, s31, 0
	global_load_dwordx4 v[28:31], v0, s[30:31]
	s_add_u32 s30, s30, 0x7e00
	s_addc_u32 s31, s31, 0
	global_load_dwordx4 v[32:35], v0, s[30:31]
	s_add_u32 s30, s30, 0x7e00
	s_addc_u32 s31, s31, 0
	global_load_dwordx4 v[36:39], v0, s[30:31]
	s_add_u32 s30, s30, 0x7e00
	s_addc_u32 s31, s31, 0
	global_load_dwordx4 v[40:43], v0, s[30:31]
	s_add_u32 s30, s30, 0x7e00
	s_addc_u32 s31, s31, 0
	global_load_dwordx4 v[44:47], v0, s[30:31]
	s_add_u32 s30, s30, 0x7e00
	s_addc_u32 s31, s31, 0
	global_load_dwordx4 v[48:51], v0, s[30:31]
	s_add_u32 s30, s30, 0x7e00
	s_addc_u32 s31, s31, 0
	global_load_dwordx4 v[52:55], v0, s[30:31]
	s_add_u32 s30, s30, 0x7e00
	s_addc_u32 s31, s31, 0
	global_load_dwordx4 v[64:67], v0, s[30:31]
	s_add_u32 s30, s30, 0x7e00
	s_addc_u32 s31, s31, 0
	global_load_dwordx4 v[68:71], v0, s[30:31]
	s_add_u32 s30, s30, 0x7e00
	s_addc_u32 s31, s31, 0
	global_load_dwordx4 v[72:75], v0, s[30:31]
	s_add_u32 s30, s30, 0x7e00
	s_addc_u32 s31, s31, 0
	global_load_dwordx4 v[76:79], v0, s[30:31]
	s_add_u32 s30, s30, 0x7e00
	s_addc_u32 s31, s31, 0
	global_load_dwordx4 v[80:83], v0, s[30:31]
	s_add_u32 s30, s30, 0x7e00
	s_addc_u32 s31, s31, 0
	global_load_dwordx4 v[84:87], v0, s[30:31]
	s_add_u32 s30, s30, 0x7e00
	s_addc_u32 s31, s31, 0
	global_load_dwordx4 v[88:91], v0, s[30:31]
	s_add_u32 s30, s30, 0x7e00
	s_addc_u32 s31, s31, 0
	global_load_dwordx4 v[92:95], v0, s[30:31]
	s_mov_b32 s2, 0x05040100
	s_mov_b32 s3, 0x07060302
	s_waitcnt vmcnt(8)
	v_perm_b32 v96, v28, v24, s2
	v_perm_b32 v97, v36, v32, s2
	v_perm_b32 v98, v44, v40, s2
	v_perm_b32 v99, v52, v48, s2
	global_store_dwordx4 v1, v[96:99], s[0:1] offset:0
	v_perm_b32 v100, v28, v24, s3
	v_perm_b32 v101, v36, v32, s3
	v_perm_b32 v102, v44, v40, s3
	v_perm_b32 v103, v52, v48, s3
	global_store_dwordx4 v1, v[100:103], s[0:1] offset:128
	v_perm_b32 v96, v29, v25, s2
	v_perm_b32 v97, v37, v33, s2
	v_perm_b32 v98, v45, v41, s2
	v_perm_b32 v99, v53, v49, s2
	global_store_dwordx4 v1, v[96:99], s[0:1] offset:256
	v_perm_b32 v100, v29, v25, s3
	v_perm_b32 v101, v37, v33, s3
	v_perm_b32 v102, v45, v41, s3
	v_perm_b32 v103, v53, v49, s3
	global_store_dwordx4 v1, v[100:103], s[0:1] offset:384
	v_perm_b32 v96, v30, v26, s2
	v_perm_b32 v97, v38, v34, s2
	v_perm_b32 v98, v46, v42, s2
	v_perm_b32 v99, v54, v50, s2
	global_store_dwordx4 v1, v[96:99], s[0:1] offset:512
	v_perm_b32 v100, v30, v26, s3
	v_perm_b32 v101, v38, v34, s3
	v_perm_b32 v102, v46, v42, s3
	v_perm_b32 v103, v54, v50, s3
	global_store_dwordx4 v1, v[100:103], s[0:1] offset:640
	v_perm_b32 v96, v31, v27, s2
	v_perm_b32 v97, v39, v35, s2
	v_perm_b32 v98, v47, v43, s2
	v_perm_b32 v99, v55, v51, s2
	global_store_dwordx4 v1, v[96:99], s[0:1] offset:768
	v_perm_b32 v100, v31, v27, s3
	v_perm_b32 v101, v39, v35, s3
	v_perm_b32 v102, v47, v43, s3
	v_perm_b32 v103, v55, v51, s3
	global_store_dwordx4 v1, v[100:103], s[0:1] offset:896
	s_waitcnt vmcnt(8)
	v_perm_b32 v96, v68, v64, s2
	v_perm_b32 v97, v76, v72, s2
	v_perm_b32 v98, v84, v80, s2
	v_perm_b32 v99, v92, v88, s2
	global_store_dwordx4 v1, v[96:99], s[0:1] offset:16
	v_perm_b32 v100, v68, v64, s3
	v_perm_b32 v101, v76, v72, s3
	v_perm_b32 v102, v84, v80, s3
	v_perm_b32 v103, v92, v88, s3
	global_store_dwordx4 v1, v[100:103], s[0:1] offset:144
	v_perm_b32 v96, v69, v65, s2
	v_perm_b32 v97, v77, v73, s2
	v_perm_b32 v98, v85, v81, s2
	v_perm_b32 v99, v93, v89, s2
	global_store_dwordx4 v1, v[96:99], s[0:1] offset:272
	v_perm_b32 v100, v69, v65, s3
	v_perm_b32 v101, v77, v73, s3
	v_perm_b32 v102, v85, v81, s3
	v_perm_b32 v103, v93, v89, s3
	global_store_dwordx4 v1, v[100:103], s[0:1] offset:400
	v_perm_b32 v96, v70, v66, s2
	v_perm_b32 v97, v78, v74, s2
	v_perm_b32 v98, v86, v82, s2
	v_perm_b32 v99, v94, v90, s2
	global_store_dwordx4 v1, v[96:99], s[0:1] offset:528
	v_perm_b32 v100, v70, v66, s3
	v_perm_b32 v101, v78, v74, s3
	v_perm_b32 v102, v86, v82, s3
	v_perm_b32 v103, v94, v90, s3
	global_store_dwordx4 v1, v[100:103], s[0:1] offset:656
	v_perm_b32 v96, v71, v67, s2
	v_perm_b32 v97, v79, v75, s2
	v_perm_b32 v98, v87, v83, s2
	v_perm_b32 v99, v95, v91, s2
	global_store_dwordx4 v1, v[96:99], s[0:1] offset:784
	v_perm_b32 v100, v71, v67, s3
	v_perm_b32 v101, v79, v75, s3
	v_perm_b32 v102, v87, v83, s3
	v_perm_b32 v103, v95, v91, s3
	global_store_dwordx4 v1, v[100:103], s[0:1] offset:912
	s_waitcnt vmcnt(0)
	s_mov_b64 exec, 0

; #define PIN16(a, o) asm volatile("" : "+v"(a[(o)+0]), "+v"(a[(o)+1]), "+v"(a[(o)+2]), "+v"(a[(o)+3]), "+v"(a[(o)+4]), "+v"(a[(o)+5]), "+v"(a[(o)+6]), "+v"(a[(o)+7]), \
;     "+v"(a[(o)+8]), "+v"(a[(o)+9]), "+v"(a[(o)+10]), "+v"(a[(o)+11]), "+v"(a[(o)+12]), "+v"(a[(o)+13]), "+v"(a[(o)+14]), "+v"(a[(o)+15]))
;     template <class Tp> __device__ __forceinline__ Tp* W(size_t off) const { return (Tp*)(ws + off); }
; __device__ void prep_gla(const Ctx& c, int ck, int blk) {
;     ...
;         const int ch = (blk - 1) * 512 + tid, h = ch >> 8, v = ch & 255;
;         bf16_t* gVT = c.W<bf16_t>(WS_GVT);
;         unsigned e[64];
; #pragma unroll
;         for (int l = 0; l < 64; ++l) e[l] = proj[(size_t)(t0 + l) * NP + C_GV + ch];
;         PIN16(e, 0); PIN16(e, 16); PIN16(e, 32); PIN16(e, 48);
.LBB0_666:
	s_or_b64 exec, exec, s[0:1]
	v_readlane_b32 s0, v249, 53
	v_readlane_b32 s1, v249, 54
	s_waitcnt vmcnt(63) expcnt(7) lgkmcnt(15)
	s_barrier
	v_lshl_add_u64 v[0:1], s[0:1], 0, v[18:19]
	v_readlane_b32 s0, v249, 57
	v_add_co_u32_e32 v0, vcc, 0x3000, v0
	v_readlane_b32 s1, v249, 58
	s_nop 0
	v_addc_co_u32_e32 v1, vcc, 0, v1, vcc
	v_lshl_add_u64 v[2:3], s[0:1], 0, v[18:19]
	v_add_co_u32_e32 v2, vcc, 0x3000, v2
	v_readlane_b32 s0, v249, 61
	s_nop 0
	v_addc_co_u32_e32 v3, vcc, 0, v3, vcc
	v_readlane_b32 s1, v249, 62
	v_ashrrev_i32_e32 v16, 8, v16
	v_lshl_add_u64 v[2:3], s[0:1], 0, v[18:19]
	v_readlane_b32 s0, v254, 1
	v_add_co_u32_e32 v2, vcc, 0x3000, v2
	v_readlane_b32 s1, v254, 2
	s_nop 0
	v_addc_co_u32_e32 v3, vcc, 0, v3, vcc
	v_lshl_add_u64 v[4:5], s[0:1], 0, v[18:19]
	v_add_co_u32_e32 v4, vcc, 0x3000, v4
	v_readlane_b32 s0, v254, 5
	s_nop 0
	v_addc_co_u32_e32 v5, vcc, 0, v5, vcc
	v_readlane_b32 s1, v254, 6
	v_and_b32_e32 v196, 0xff, v144
	v_lshl_add_u64 v[4:5], s[0:1], 0, v[18:19]
	v_readlane_b32 s0, v254, 9
	v_add_co_u32_e32 v4, vcc, 0x3000, v4
	v_readlane_b32 s1, v254, 10
	s_nop 0
	v_addc_co_u32_e32 v5, vcc, 0, v5, vcc
	v_lshl_add_u64 v[6:7], s[0:1], 0, v[18:19]
	v_add_co_u32_e32 v6, vcc, 0x3000, v6
	v_readlane_b32 s0, v254, 13
	s_nop 0
	v_addc_co_u32_e32 v7, vcc, 0, v7, vcc
	v_readlane_b32 s1, v254, 14
	v_cmp_gt_u32_e64 s[72:73], 64, v196
	v_lshl_add_u64 v[6:7], s[0:1], 0, v[18:19]
	v_readlane_b32 s0, v254, 17
	v_add_co_u32_e32 v6, vcc, 0x3000, v6
	v_readlane_b32 s1, v254, 18
	s_nop 0
	v_addc_co_u32_e32 v7, vcc, 0, v7, vcc
	v_lshl_add_u64 v[8:9], s[0:1], 0, v[18:19]
	v_add_co_u32_e32 v8, vcc, 0x3000, v8
	v_readlane_b32 s0, v254, 21
	s_nop 0
	v_addc_co_u32_e32 v9, vcc, 0, v9, vcc
	v_readlane_b32 s1, v254, 22
	s_nop 0
	v_lshl_add_u64 v[8:9], s[0:1], 0, v[18:19]
	v_readlane_b32 s0, v254, 25
	v_add_co_u32_e32 v8, vcc, 0x3000, v8
	v_readlane_b32 s1, v254, 26
	s_nop 0
	v_addc_co_u32_e32 v9, vcc, 0, v9, vcc
	v_lshl_add_u64 v[10:11], s[0:1], 0, v[18:19]
	v_add_co_u32_e32 v10, vcc, 0x3000, v10
	v_readlane_b32 s0, v254, 29
	s_nop 0
	v_addc_co_u32_e32 v11, vcc, 0, v11, vcc
	v_readlane_b32 s1, v254, 30
	s_nop 0
	v_lshl_add_u64 v[10:11], s[0:1], 0, v[18:19]
	v_readlane_b32 s0, v254, 35
	v_add_co_u32_e32 v10, vcc, 0x3000, v10
	v_readlane_b32 s1, v254, 36
	s_nop 0
	v_addc_co_u32_e32 v11, vcc, 0, v11, vcc
	v_lshl_add_u64 v[12:13], s[0:1], 0, v[18:19]
	v_add_co_u32_e32 v12, vcc, 0x3000, v12
	v_readlane_b32 s0, v254, 39
	s_nop 0
	v_addc_co_u32_e32 v13, vcc, 0, v13, vcc
	v_readlane_b32 s1, v254, 40
	s_nop 0
	v_lshl_add_u64 v[12:13], s[0:1], 0, v[18:19]
	v_readlane_b32 s0, v254, 43
	v_add_co_u32_e32 v12, vcc, 0x3000, v12
	v_readlane_b32 s1, v254, 44
	s_nop 0
	v_addc_co_u32_e32 v13, vcc, 0, v13, vcc
	v_lshl_add_u64 v[14:15], s[0:1], 0, v[18:19]
	v_add_co_u32_e32 v14, vcc, 0x3000, v14
	v_readlane_b32 s0, v254, 47
	s_nop 0
	v_addc_co_u32_e32 v15, vcc, 0, v15, vcc
	v_readlane_b32 s1, v254, 48
	s_nop 0
	v_lshl_add_u64 v[14:15], s[0:1], 0, v[18:19]
	v_readlane_b32 s0, v254, 51
	v_add_co_u32_e32 v14, vcc, 0x3000, v14
	v_readlane_b32 s1, v254, 52
	s_nop 0
	v_addc_co_u32_e32 v15, vcc, 0, v15, vcc
	v_lshl_add_u64 v[22:23], s[0:1], 0, v[18:19]
	v_add_co_u32_e32 v22, vcc, 0x3000, v22
	v_readlane_b32 s0, v254, 55
	s_nop 0
	v_addc_co_u32_e32 v23, vcc, 0, v23, vcc
	v_readlane_b32 s1, v254, 56
	s_nop 0
	v_lshl_add_u64 v[22:23], s[0:1], 0, v[18:19]
	v_add_co_u32_e32 v22, vcc, 0x3000, v22
	v_readlane_b32 s0, v254, 59
	s_nop 0
	v_addc_co_u32_e32 v23, vcc, 0, v23, vcc
	v_readlane_b32 s1, v254, 60
	s_nop 0
	v_lshl_add_u64 v[22:23], s[0:1], 0, v[18:19]
	v_add_co_u32_e32 v22, vcc, 0x3000, v22
	v_readlane_b32 s0, v254, 63
	s_nop 0
	v_addc_co_u32_e32 v23, vcc, 0, v23, vcc
	v_readlane_b32 s1, v250, 0
	s_nop 0
	v_lshl_add_u64 v[22:23], s[0:1], 0, v[18:19]
	v_readlane_b32 s0, v250, 3
	v_add_co_u32_e32 v22, vcc, 0x3000, v22
	v_readlane_b32 s1, v250, 4
	s_nop 0
	v_addc_co_u32_e32 v23, vcc, 0, v23, vcc
	v_lshl_add_u64 v[24:25], s[0:1], 0, v[18:19]
	v_add_co_u32_e32 v24, vcc, 0x3000, v24
	v_readlane_b32 s0, v250, 7
	s_nop 0
	v_addc_co_u32_e32 v25, vcc, 0, v25, vcc
	v_readlane_b32 s1, v250, 8
	s_nop 0
	v_lshl_add_u64 v[24:25], s[0:1], 0, v[18:19]
	v_readlane_b32 s0, v250, 11
	v_add_co_u32_e32 v24, vcc, 0x3000, v24
	v_readlane_b32 s1, v250, 12
	s_nop 0
	v_addc_co_u32_e32 v25, vcc, 0, v25, vcc
	v_lshl_add_u64 v[26:27], s[0:1], 0, v[18:19]
	v_add_co_u32_e32 v26, vcc, 0x3000, v26
	v_readlane_b32 s0, v250, 15
	s_nop 0
	v_addc_co_u32_e32 v27, vcc, 0, v27, vcc
	v_readlane_b32 s1, v250, 16
	s_nop 0
	v_lshl_add_u64 v[26:27], s[0:1], 0, v[18:19]
	v_readlane_b32 s0, v250, 19
	v_add_co_u32_e32 v26, vcc, 0x3000, v26
	v_readlane_b32 s1, v250, 20
	s_nop 0
	v_addc_co_u32_e32 v27, vcc, 0, v27, vcc
	v_lshl_add_u64 v[28:29], s[0:1], 0, v[18:19]
	v_add_co_u32_e32 v28, vcc, 0x3000, v28
	v_readlane_b32 s0, v250, 23
	s_nop 0
	v_addc_co_u32_e32 v29, vcc, 0, v29, vcc
	v_readlane_b32 s1, v250, 24
	s_nop 0
	v_lshl_add_u64 v[28:29], s[0:1], 0, v[18:19]
	v_readlane_b32 s0, v250, 27
	v_add_co_u32_e32 v28, vcc, 0x3000, v28
	v_readlane_b32 s1, v250, 28
	s_nop 0
	v_addc_co_u32_e32 v29, vcc, 0, v29, vcc
	v_lshl_add_u64 v[30:31], s[0:1], 0, v[18:19]
	v_add_co_u32_e32 v30, vcc, 0x3000, v30
	v_readlane_b32 s0, v250, 31
	s_nop 0
	v_addc_co_u32_e32 v31, vcc, 0, v31, vcc
	v_readlane_b32 s1, v250, 32
	s_nop 0
	v_lshl_add_u64 v[30:31], s[0:1], 0, v[18:19]
	v_readlane_b32 s0, v250, 35
	v_add_co_u32_e32 v30, vcc, 0x3000, v30
	v_readlane_b32 s1, v250, 36
	s_nop 0
	v_addc_co_u32_e32 v31, vcc, 0, v31, vcc
	v_lshl_add_u64 v[32:33], s[0:1], 0, v[18:19]
	v_add_co_u32_e32 v32, vcc, 0x3000, v32
	v_readlane_b32 s0, v250, 39
; #define PIN16(a, o) asm volatile("" : "+v"(a[(o)+0]), "+v"(a[(o)+1]), "+v"(a[(o)+2]), "+v"(a[(o)+3]), "+v"(a[(o)+4]), "+v"(a[(o)+5]), "+v"(a[(o)+6]), "+v"(a[(o)+7]), \
;     "+v"(a[(o)+8]), "+v"(a[(o)+9]), "+v"(a[(o)+10]), "+v"(a[(o)+11]), "+v"(a[(o)+12]), "+v"(a[(o)+13]), "+v"(a[(o)+14]), "+v"(a[(o)+15]))
; __device__ void prep_gla(const Ctx& c, int ck, int blk) {
;     ...
;         unsigned e[64];
; #pragma unroll
;         for (int l = 0; l < 64; ++l) e[l] = proj[(size_t)(t0 + l) * NP + C_GV + ch];
;         PIN16(e, 0); PIN16(e, 16); PIN16(e, 32); PIN16(e, 48);
	s_nop 0
	v_addc_co_u32_e32 v33, vcc, 0, v33, vcc
	v_readlane_b32 s1, v250, 40
	s_nop 0
	v_lshl_add_u64 v[32:33], s[0:1], 0, v[18:19]
	v_readlane_b32 s0, v250, 43
	v_add_co_u32_e32 v32, vcc, 0x3000, v32
	v_readlane_b32 s1, v250, 44
	s_nop 0
	v_addc_co_u32_e32 v33, vcc, 0, v33, vcc
	v_lshl_add_u64 v[34:35], s[0:1], 0, v[18:19]
	v_add_co_u32_e32 v34, vcc, 0x3000, v34
	v_readlane_b32 s0, v250, 47
	s_nop 0
	v_addc_co_u32_e32 v35, vcc, 0, v35, vcc
	v_readlane_b32 s1, v250, 48
	s_nop 0
	v_lshl_add_u64 v[34:35], s[0:1], 0, v[18:19]
	v_readlane_b32 s0, v250, 51
	v_add_co_u32_e32 v34, vcc, 0x3000, v34
	v_readlane_b32 s1, v250, 52
	s_nop 0
	v_addc_co_u32_e32 v35, vcc, 0, v35, vcc
	v_lshl_add_u64 v[36:37], s[0:1], 0, v[18:19]
	v_add_co_u32_e32 v36, vcc, 0x3000, v36
	v_readlane_b32 s0, v250, 55
	s_nop 0
	v_addc_co_u32_e32 v37, vcc, 0, v37, vcc
	v_readlane_b32 s1, v250, 56
	s_nop 0
	v_lshl_add_u64 v[36:37], s[0:1], 0, v[18:19]
	v_readlane_b32 s0, v250, 59
	v_add_co_u32_e32 v36, vcc, 0x3000, v36
	v_readlane_b32 s1, v250, 60
	s_nop 0
	v_addc_co_u32_e32 v37, vcc, 0, v37, vcc
	v_lshl_add_u64 v[38:39], s[0:1], 0, v[18:19]
	v_add_co_u32_e32 v38, vcc, 0x3000, v38
	v_readlane_b32 s0, v251, 1
	s_nop 0
	v_addc_co_u32_e32 v39, vcc, 0, v39, vcc
	v_readlane_b32 s1, v251, 2
	s_nop 0
	v_lshl_add_u64 v[38:39], s[0:1], 0, v[18:19]
	v_readlane_b32 s0, v251, 5
	v_add_co_u32_e32 v38, vcc, 0x3000, v38
	v_readlane_b32 s1, v251, 6
	s_nop 0
	v_addc_co_u32_e32 v39, vcc, 0, v39, vcc
	v_lshl_add_u64 v[40:41], s[0:1], 0, v[18:19]
	v_add_co_u32_e32 v40, vcc, 0x3000, v40
	v_readlane_b32 s0, v251, 9
	s_nop 0
	v_addc_co_u32_e32 v41, vcc, 0, v41, vcc
	v_readlane_b32 s1, v251, 10
	s_nop 0
	v_lshl_add_u64 v[40:41], s[0:1], 0, v[18:19]
	v_readlane_b32 s0, v251, 13
	v_add_co_u32_e32 v40, vcc, 0x3000, v40
	v_readlane_b32 s1, v251, 14
	s_nop 0
	v_addc_co_u32_e32 v41, vcc, 0, v41, vcc
	v_lshl_add_u64 v[42:43], s[0:1], 0, v[18:19]
	v_add_co_u32_e32 v42, vcc, 0x3000, v42
	v_readlane_b32 s0, v251, 17
	s_nop 0
	v_addc_co_u32_e32 v43, vcc, 0, v43, vcc
	v_readlane_b32 s1, v251, 18
	s_nop 0
	v_lshl_add_u64 v[42:43], s[0:1], 0, v[18:19]
	v_readlane_b32 s0, v251, 21
	v_add_co_u32_e32 v42, vcc, 0x3000, v42
	v_readlane_b32 s1, v251, 22
	s_nop 0
	v_addc_co_u32_e32 v43, vcc, 0, v43, vcc
	v_lshl_add_u64 v[44:45], s[0:1], 0, v[18:19]
	v_add_co_u32_e32 v44, vcc, 0x3000, v44
	v_readlane_b32 s0, v251, 25
	s_nop 0
	v_addc_co_u32_e32 v45, vcc, 0, v45, vcc
	v_readlane_b32 s1, v251, 26
	s_nop 0
	v_lshl_add_u64 v[44:45], s[0:1], 0, v[18:19]
	v_add_co_u32_e32 v44, vcc, 0x3000, v44
	v_readlane_b32 s0, v251, 31
	s_nop 0
	v_addc_co_u32_e32 v45, vcc, 0, v45, vcc
	v_readlane_b32 s1, v251, 32
	s_nop 0
	v_lshl_add_u64 v[44:45], s[0:1], 0, v[18:19]
	v_add_co_u32_e32 v44, vcc, 0x3000, v44
	v_readlane_b32 s0, v251, 37
	s_nop 0
	v_addc_co_u32_e32 v45, vcc, 0, v45, vcc
	v_readlane_b32 s1, v251, 38
	s_nop 0
	v_lshl_add_u64 v[44:45], s[0:1], 0, v[18:19]
	v_add_co_u32_e32 v44, vcc, 0x3000, v44
	v_readlane_b32 s0, v251, 43
	s_nop 0
	v_addc_co_u32_e32 v45, vcc, 0, v45, vcc
	v_readlane_b32 s1, v251, 44
	s_nop 0
	v_lshl_add_u64 v[44:45], s[0:1], 0, v[18:19]
	v_add_co_u32_e32 v44, vcc, 0x3000, v44
	v_readlane_b32 s0, v251, 49
	s_nop 0
	v_addc_co_u32_e32 v45, vcc, 0, v45, vcc
	v_readlane_b32 s1, v251, 50
	s_nop 0
	v_lshl_add_u64 v[44:45], s[0:1], 0, v[18:19]
	v_add_co_u32_e32 v44, vcc, 0x3000, v44
	v_readlane_b32 s0, v251, 55
	s_nop 0
	v_addc_co_u32_e32 v45, vcc, 0, v45, vcc
	v_readlane_b32 s1, v251, 56
	s_nop 0
	v_lshl_add_u64 v[44:45], s[0:1], 0, v[18:19]
	v_add_co_u32_e32 v44, vcc, 0x3000, v44
	v_readlane_b32 s0, v251, 61
	s_nop 0
	v_addc_co_u32_e32 v45, vcc, 0, v45, vcc
	v_readlane_b32 s1, v251, 62
	s_nop 0
	v_lshl_add_u64 v[44:45], s[0:1], 0, v[18:19]
	v_add_co_u32_e32 v44, vcc, 0x3000, v44
	v_readlane_b32 s0, v252, 1
	s_nop 0
	v_addc_co_u32_e32 v45, vcc, 0, v45, vcc
	v_readlane_b32 s1, v252, 2
	s_nop 0
	v_lshl_add_u64 v[44:45], s[0:1], 0, v[18:19]
	v_add_co_u32_e32 v44, vcc, 0x3000, v44
	v_readlane_b32 s0, v252, 7
	s_nop 0
	v_addc_co_u32_e32 v45, vcc, 0, v45, vcc
	v_readlane_b32 s1, v252, 8
	s_nop 0
	v_lshl_add_u64 v[44:45], s[0:1], 0, v[18:19]
	v_add_co_u32_e32 v44, vcc, 0x3000, v44
	v_readlane_b32 s0, v252, 13
	s_nop 0
	v_addc_co_u32_e32 v45, vcc, 0, v45, vcc
	v_readlane_b32 s1, v252, 14
	s_nop 0
	v_lshl_add_u64 v[44:45], s[0:1], 0, v[18:19]
	v_add_co_u32_e32 v44, vcc, 0x3000, v44
	v_readlane_b32 s0, v252, 19
	s_nop 0
	v_addc_co_u32_e32 v45, vcc, 0, v45, vcc
	v_readlane_b32 s1, v252, 20
	s_nop 0
	v_lshl_add_u64 v[44:45], s[0:1], 0, v[18:19]
	v_add_co_u32_e32 v44, vcc, 0x3000, v44
	v_readlane_b32 s0, v252, 25
	s_nop 0
	v_addc_co_u32_e32 v45, vcc, 0, v45, vcc
	v_readlane_b32 s1, v252, 26
	s_nop 0
	v_lshl_add_u64 v[44:45], s[0:1], 0, v[18:19]
	v_add_co_u32_e32 v44, vcc, 0x3000, v44
	v_readlane_b32 s0, v252, 31
	s_nop 0
	v_addc_co_u32_e32 v45, vcc, 0, v45, vcc
	v_readlane_b32 s1, v252, 32
	s_nop 0
	v_lshl_add_u64 v[44:45], s[0:1], 0, v[18:19]
	v_add_co_u32_e32 v44, vcc, 0x3000, v44
	v_readlane_b32 s0, v252, 35
	s_nop 0
	v_addc_co_u32_e32 v45, vcc, 0, v45, vcc
	v_readlane_b32 s1, v252, 36
	s_nop 0
	v_lshl_add_u64 v[44:45], s[0:1], 0, v[18:19]
	v_add_co_u32_e32 v44, vcc, 0x3000, v44
	v_readlane_b32 s0, v252, 39
	s_nop 0
	v_addc_co_u32_e32 v45, vcc, 0, v45, vcc
	v_readlane_b32 s1, v252, 40
	s_nop 0
	v_lshl_add_u64 v[44:45], s[0:1], 0, v[18:19]
	v_add_co_u32_e32 v44, vcc, 0x3000, v44
	v_readlane_b32 s0, v252, 43
	s_nop 0
	v_addc_co_u32_e32 v45, vcc, 0, v45, vcc
	v_readlane_b32 s1, v252, 44
	s_nop 0
	v_lshl_add_u64 v[44:45], s[0:1], 0, v[18:19]
	v_add_co_u32_e32 v44, vcc, 0x3000, v44
	v_readlane_b32 s0, v252, 47
	s_nop 0
; __device__ __forceinline__ float bf2f(bf16_t b) { return __uint_as_float(((unsigned)b) << 16); }
; __device__ __forceinline__ float sigmoidf_(float x) { return __builtin_amdgcn_rcpf(1.0f + __expf(-x)); }
; __device__ __forceinline__ float softplusf_(float x) { return fmaxf(x, 0.f) + __logf(1.0f + __expf(-fabsf(x))); }
; #define PIN16(a, o) asm volatile("" : "+v"(a[(o)+0]), "+v"(a[(o)+1]), "+v"(a[(o)+2]), "+v"(a[(o)+3]), "+v"(a[(o)+4]), "+v"(a[(o)+5]), "+v"(a[(o)+6]), "+v"(a[(o)+7]), \
;     "+v"(a[(o)+8]), "+v"(a[(o)+9]), "+v"(a[(o)+10]), "+v"(a[(o)+11]), "+v"(a[(o)+12]), "+v"(a[(o)+13]), "+v"(a[(o)+14]), "+v"(a[(o)+15]))
;     template <class Tp> __device__ __forceinline__ Tp* W(size_t off) const { return (Tp*)(ws + off); }
; __device__ void prep_gla(const Ctx& c, int ck, int blk) {
;     ...
;         const int ch = (blk - 1) * 512 + tid, h = ch >> 8, v = ch & 255;
;         bf16_t* gVT = c.W<bf16_t>(WS_GVT);
;         unsigned e[64];
; #pragma unroll
;         for (int l = 0; l < 64; ++l) e[l] = proj[(size_t)(t0 + l) * NP + C_GV + ch];
;         PIN16(e, 0); PIN16(e, 16); PIN16(e, 32); PIN16(e, 48);
; #pragma unroll
;         for (int l0 = 0; l0 < 64; l0 += 8) {
;             u32x4 a; a.x = e[l0] | (e[l0 + 1] << 16); a.y = e[l0 + 2] | (e[l0 + 3] << 16); a.z = e[l0 + 4] | (e[l0 + 5] << 16); a.w = e[l0 + 6] | (e[l0 + 7] << 16);
;             *(u32x4*)(gVT + ((size_t)(ck * 4 + h) * 256 + v) * 64 + l0) = a;
;         }
; __device__ void dn_d1(const Ctx& c, int ip) {
;     ...
;     __syncthreads();
;     if (lt < 64) { const size_t rb = (size_t)(t0 + lt) * NP;
;         beta_s[lt] = sigmoidf_(bf2f(proj[rb + C_DNB + h]));
;         float g = -__expf(c.in(I_DNALOG)[c.layer * 8 + h]) * softplusf_(bf2f(proj[rb + C_DNA + h]) + c.in(I_DNDTB)[c.layer * 8 + h]);
; #pragma unroll
;         for (int d = 1; d < 64; d <<= 1) { const float o = __shfl_up(g, d); if ((lt & 63) >= d) g += o; }
;         gc_s[lt] = g; }
	v_addc_co_u32_e32 v45, vcc, 0, v45, vcc
	v_readlane_b32 s1, v252, 48
	s_nop 0
	v_lshl_add_u64 v[44:45], s[0:1], 0, v[18:19]
	v_add_co_u32_e32 v44, vcc, 0x3000, v44
	v_readlane_b32 s0, v252, 51
	s_nop 0
	v_addc_co_u32_e32 v45, vcc, 0, v45, vcc
	v_readlane_b32 s1, v252, 52
	s_nop 0
	v_lshl_add_u64 v[44:45], s[0:1], 0, v[18:19]
	v_add_co_u32_e32 v44, vcc, 0x3000, v44
	v_readlane_b32 s0, v252, 57
	s_nop 0
	v_addc_co_u32_e32 v45, vcc, 0, v45, vcc
	v_readlane_b32 s1, v252, 58
	s_nop 0
	v_lshl_add_u64 v[44:45], s[0:1], 0, v[18:19]
	v_add_co_u32_e32 v44, vcc, 0x3000, v44
	v_readlane_b32 s0, v252, 63
	s_nop 0
	v_addc_co_u32_e32 v45, vcc, 0, v45, vcc
	v_readlane_b32 s1, v253, 0
	s_nop 0
	v_lshl_add_u64 v[44:45], s[0:1], 0, v[18:19]
	v_add_co_u32_e32 v44, vcc, 0x3000, v44
	v_readlane_b32 s0, v253, 5
	s_nop 0
	v_addc_co_u32_e32 v45, vcc, 0, v45, vcc
	v_readlane_b32 s1, v253, 6
	s_nop 0
	v_lshl_add_u64 v[44:45], s[0:1], 0, v[18:19]
	v_add_co_u32_e32 v44, vcc, 0x3000, v44
	v_readlane_b32 s0, v253, 11
	s_nop 0
	v_addc_co_u32_e32 v45, vcc, 0, v45, vcc
	v_readlane_b32 s1, v253, 12
	s_nop 0
	v_lshl_add_u64 v[44:45], s[0:1], 0, v[18:19]
	v_add_co_u32_e32 v44, vcc, 0x3000, v44
	v_readlane_b32 s0, v253, 17
	s_nop 0
	v_addc_co_u32_e32 v45, vcc, 0, v45, vcc
	v_readlane_b32 s1, v253, 18
	s_nop 0
	v_lshl_add_u64 v[44:45], s[0:1], 0, v[18:19]
	v_readlane_b32 s0, v253, 23
	v_add_co_u32_e32 v44, vcc, 0x3000, v44
	v_readlane_b32 s1, v253, 24
	s_nop 0
	v_addc_co_u32_e32 v45, vcc, 0, v45, vcc
	v_lshl_add_u64 v[18:19], s[0:1], 0, v[18:19]
	v_add_co_u32_e32 v18, vcc, 0x3000, v18
	s_nop 0
	v_addc_co_u32_e32 v19, vcc, 0, v19, vcc
	v_add_u32_e32 v18, v151, v16
	v_ashrrev_i32_e32 v19, 31, v18
	v_readlane_b32 s0, v249, 5
	v_and_b32_e32 v16, 0x3fc0, v20
	v_lshlrev_b64 v[18:19], 15, v[18:19]
	v_readlane_b32 s1, v249, 6
	s_waitcnt vmcnt(48)
	v_lshlrev_b32_e32 v176, 1, v16
	v_lshl_or_b32 v0, v1, 16, v0
	v_lshl_add_u64 v[18:19], s[0:1], 0, v[18:19]
	v_lshl_add_u64 v[18:19], v[18:19], 0, v[176:177]
	v_lshl_or_b32 v1, v3, 16, v2
	v_lshl_or_b32 v2, v5, 16, v4
	v_lshl_or_b32 v3, v7, 16, v6
	s_waitcnt vmcnt(32)
	s_waitcnt vmcnt(16)
	s_waitcnt vmcnt(0)
	v_readlane_b32 s0, v249, 37
	s_lshl_b32 s39, s0, 1
	v_lshl_or_b32 v0, v9, 16, v8
	v_lshl_or_b32 v1, v11, 16, v10
	v_lshl_or_b32 v2, v13, 16, v12
	v_lshl_or_b32 v3, v15, 16, v14
	s_movk_i32 s0, 0x4600
	s_nop 0
	v_lshl_or_b32 v0, v21, 16, v17
	v_lshl_or_b32 v1, v23, 16, v22
	v_lshl_or_b32 v2, v25, 16, v24
	v_lshl_or_b32 v3, v27, 16, v26
	s_nop 1
	v_lshl_or_b32 v0, v29, 16, v28
	v_lshl_or_b32 v1, v31, 16, v30
	v_lshl_or_b32 v2, v33, 16, v32
	v_lshl_or_b32 v3, v35, 16, v34
	s_nop 1
	v_lshl_or_b32 v0, v37, 16, v36
	v_lshl_or_b32 v1, v39, 16, v38
	v_lshl_or_b32 v2, v41, 16, v40
	v_lshl_or_b32 v3, v43, 16, v42
	s_nop 1
	v_lshl_or_b32 v0, v47, 16, v46
	v_lshl_or_b32 v1, v49, 16, v48
	v_lshl_or_b32 v2, v51, 16, v50
	v_lshl_or_b32 v3, v53, 16, v52
	s_nop 1
	v_lshl_or_b32 v0, v55, 16, v54
	v_lshl_or_b32 v1, v57, 16, v56
	v_lshl_or_b32 v2, v59, 16, v58
	v_lshl_or_b32 v3, v63, 16, v61
	s_nop 1
	v_lshl_or_b32 v0, v66, 16, v65
	v_lshl_or_b32 v1, v68, 16, v67
	v_lshl_or_b32 v2, v70, 16, v69
	v_lshl_or_b32 v3, v45, 16, v44
	s_barrier
	s_nop 0
	v_or_b32_e32 v0, s39, v151
	v_ashrrev_i32_e32 v1, 8, v144
	v_lshl_add_u32 v70, v0, 1, v1
	v_lshlrev_b32_e32 v0, 3, v70
	v_mad_i32_i24 v157, v1, s0, 0
	v_and_b32_e32 v61, 7, v70
	v_and_b32_e32 v54, 0xffffffc0, v0
	v_lshl_add_u32 v197, v196, 2, v157
	s_barrier
	s_and_saveexec_b64 s[0:1], s[72:73]
	s_cbranch_execz .LBB0_668
	v_or_b32_e32 v2, v54, v196
	v_mov_b64_e32 v[0:1], s[28:29]
	v_mad_i64_i32 v[0:1], s[2:3], v2, s6, v[0:1]
	s_load_dwordx4 s[4:7], s[94:95], 0x28
	v_lshlrev_b32_e32 v176, 1, v61
	v_readlane_b32 s2, v249, 7
	v_lshl_add_u64 v[0:1], v[0:1], 0, v[176:177]
	v_add_co_u32_e32 v0, vcc, 0x1000, v0
	v_or_b32_e32 v2, s2, v61
	v_ashrrev_i32_e32 v3, 31, v2
	v_addc_co_u32_e32 v1, vcc, 0, v1, vcc
	v_lshlrev_b64 v[2:3], 2, v[2:3]
	global_load_ushort v6, v[0:1], off offset:2064
	s_waitcnt lgkmcnt(0)
	v_lshl_add_u64 v[4:5], s[6:7], 0, v[2:3]
	global_load_dword v4, v[4:5], off
	v_lshl_add_u64 v[2:3], s[4:5], 0, v[2:3]
	global_load_dword v2, v[2:3], off
	s_nop 0
	global_load_ushort v0, v[0:1], off offset:2048
	s_waitcnt vmcnt(3)
	v_lshlrev_b32_e32 v1, 16, v6
	s_waitcnt vmcnt(2)
	v_add_f32_e32 v1, v4, v1
	v_mul_f32_e64 v3, |v1|, s57
	v_exp_f32_e32 v3, v3
	s_waitcnt vmcnt(1)
	v_mul_f32_e32 v2, 0x3fb8aa3b, v2
	v_exp_f32_e32 v2, v2
	v_max_f32_e32 v1, 0, v1
	v_add_f32_e32 v3, 1.0, v3
	v_cmp_gt_f32_e32 vcc, s59, v3
	s_waitcnt vmcnt(0)
	v_lshlrev_b32_e32 v0, 16, v0
	v_mul_f32_e32 v0, 0xbfb8aa3b, v0
	v_cndmask_b32_e64 v4, 0, 32, vcc
	v_ldexp_f32 v3, v3, v4
	v_log_f32_e32 v3, v3
	v_cndmask_b32_e32 v4, 0, v240, vcc
	v_exp_f32_e32 v0, v0
	v_mul_f32_e32 v5, 0x3f317217, v3
	v_fma_f32 v5, v3, s60, -v5
	v_fmac_f32_e32 v5, 0x3377d1cf, v3
	v_fmac_f32_e32 v5, 0x3f317217, v3
	v_cmp_lt_f32_e64 vcc, |v3|, s61
	v_add_f32_e32 v0, 1.0, v0
	v_rcp_f32_e32 v0, v0
	v_cndmask_b32_e32 v3, v3, v5, vcc
	v_sub_f32_e32 v3, v3, v4
	v_add_f32_e32 v1, v1, v3
	v_mul_f32_e64 v3, v1, -v2
	ds_bpermute_b32 v4, v145, v3
	v_cmp_eq_u32_e32 vcc, 0, v196
	s_waitcnt lgkmcnt(0)
	v_fma_f32 v1, v1, -v2, v4
	v_cndmask_b32_e32 v1, v1, v3, vcc
	ds_bpermute_b32 v2, v146, v1
	v_cmp_gt_u32_e32 vcc, 2, v196
	s_waitcnt lgkmcnt(0)
	v_add_f32_e32 v2, v1, v2
	v_cndmask_b32_e32 v1, v2, v1, vcc
	ds_bpermute_b32 v2, v147, v1
	v_cmp_gt_u32_e32 vcc, 4, v196
	s_waitcnt lgkmcnt(0)
	v_add_f32_e32 v2, v1, v2
	v_cndmask_b32_e32 v1, v2, v1, vcc
	ds_bpermute_b32 v2, v148, v1
	v_cmp_gt_u32_e32 vcc, 8, v196
	s_waitcnt lgkmcnt(0)
	v_add_f32_e32 v2, v1, v2
	v_cndmask_b32_e32 v1, v2, v1, vcc
	ds_bpermute_b32 v2, v149, v1
	v_cmp_gt_u32_e32 vcc, 16, v196
	s_waitcnt lgkmcnt(0)
	v_add_f32_e32 v2, v1, v2
	v_cndmask_b32_e32 v1, v2, v1, vcc
	ds_bpermute_b32 v2, v150, v1
	v_cmp_gt_u32_e32 vcc, 32, v196
	s_waitcnt lgkmcnt(0)
	v_add_f32_e32 v2, v1, v2
	v_cndmask_b32_e32 v1, v2, v1, vcc
	ds_write2st64_b32 v197, v0, v1 offset0:68 offset1:69
